# v25 + attention unit epilogue: the four dependent shfl_xor steps of each row's sum of squares use DPP lane movement instead of ds_bpermute round trips
# speedup vs baseline: 1.0166x; 1.0074x over previous
; __device__ __forceinline__ void attn_unit(int b, int h, int qb, const bf16* Q, const bf16* K, const bf16* V, bf16* MIX, LAS unsigned char* lds, const LAS float* BLh, float lam, LAS float* als, gu32* rdy4) {
;     ...
;             for (int r = 0; r < 16; ++r) o[d][r] = o[d][r] * rl[r] - lam * stg[(d * 16 + r) * 64 + lane];
.LBB0_647:
	s_waitcnt lgkmcnt(0)
	s_barrier
	s_cmpk_gt_u32 s68, 0xff
	s_cbranch_scc1 .LBB0_652
	ds_read2st64_b32 v[84:85], v74 offset1:1
	ds_read2st64_b32 v[86:87], v74 offset0:2 offset1:3
	ds_read2st64_b32 v[88:89], v74 offset0:4 offset1:5
	ds_read2st64_b32 v[90:91], v74 offset0:6 offset1:7
	s_lshl_b32 s19, s67, 11
	s_waitcnt lgkmcnt(3)
	v_mul_f32_e32 v83, v174, v84
	v_mul_f32_e32 v84, v174, v85
	v_fma_f32 v50, v50, v82, -v83
	s_waitcnt lgkmcnt(2)
	v_mul_f32_e32 v83, v174, v86
	v_fma_f32 v51, v51, v80, -v84
	v_fma_f32 v52, v52, v79, -v83
	v_mul_f32_e32 v83, v174, v87
	ds_read2st64_b32 v[84:85], v74 offset0:8 offset1:9
	v_fma_f32 v53, v53, v78, -v83
	s_waitcnt lgkmcnt(2)
	v_mul_f32_e32 v83, v174, v88
	v_fma_f32 v54, v54, v77, -v83
	v_mul_f32_e32 v83, v174, v89
	v_fma_f32 v55, v55, v81, -v83
	s_waitcnt lgkmcnt(1)
	v_mul_f32_e32 v83, v174, v90
	v_fma_f32 v56, v56, v76, -v83
	v_mul_f32_e32 v83, v174, v91
	ds_read2st64_b32 v[86:87], v74 offset0:10 offset1:11
	ds_read2st64_b32 v[88:89], v74 offset0:12 offset1:13
	ds_read2st64_b32 v[90:91], v74 offset0:14 offset1:15
	v_fma_f32 v57, v57, v75, -v83
	s_waitcnt lgkmcnt(3)
	v_mul_f32_e32 v83, v174, v84
	v_fma_f32 v58, v58, v73, -v83
	v_mul_f32_e32 v83, v174, v85
	v_fma_f32 v59, v59, v72, -v83
	s_waitcnt lgkmcnt(2)
	v_mul_f32_e32 v83, v174, v86
	v_fma_f32 v60, v60, v71, -v83
	v_mul_f32_e32 v83, v174, v87
	ds_read2st64_b32 v[84:85], v74 offset0:16 offset1:17
	v_fma_f32 v61, v61, v70, -v83
	s_waitcnt lgkmcnt(2)
	v_mul_f32_e32 v83, v174, v88
	v_fma_f32 v62, v62, v69, -v83
	v_mul_f32_e32 v83, v174, v89
	v_fma_f32 v63, v63, v68, -v83
	s_waitcnt lgkmcnt(1)
	v_mul_f32_e32 v83, v174, v90
	v_fma_f32 v64, v64, v67, -v83
	v_mul_f32_e32 v83, v174, v91
	ds_read2st64_b32 v[86:87], v74 offset0:18 offset1:19
	ds_read2st64_b32 v[88:89], v74 offset0:20 offset1:21
	ds_read2st64_b32 v[90:91], v74 offset0:22 offset1:23
	v_fma_f32 v65, v65, v66, -v83
	s_waitcnt lgkmcnt(3)
	v_mul_f32_e32 v83, v174, v84
	v_fma_f32 v34, v34, v82, -v83
	v_mul_f32_e32 v83, v174, v85
	v_fma_f32 v35, v35, v80, -v83
	s_waitcnt lgkmcnt(2)
	v_mul_f32_e32 v83, v174, v86
	v_fma_f32 v36, v36, v79, -v83
	v_mul_f32_e32 v83, v174, v87
	ds_read2st64_b32 v[84:85], v74 offset0:24 offset1:25
	v_fma_f32 v37, v37, v78, -v83
	s_waitcnt lgkmcnt(2)
	v_mul_f32_e32 v83, v174, v88
	v_fma_f32 v38, v38, v77, -v83
	v_mul_f32_e32 v83, v174, v89
	v_fma_f32 v39, v39, v81, -v83
	s_waitcnt lgkmcnt(1)
	v_mul_f32_e32 v83, v174, v90
	v_fma_f32 v40, v40, v76, -v83
	v_mul_f32_e32 v83, v174, v91
	ds_read2st64_b32 v[86:87], v74 offset0:26 offset1:27
	ds_read2st64_b32 v[88:89], v74 offset0:28 offset1:29
	ds_read2st64_b32 v[90:91], v74 offset0:30 offset1:31
	v_fma_f32 v41, v41, v75, -v83
	s_waitcnt lgkmcnt(3)
	v_mul_f32_e32 v83, v174, v84
	v_fma_f32 v83, v42, v73, -v83
	v_mul_f32_e32 v42, v174, v85
	v_fma_f32 v84, v43, v72, -v42
	s_waitcnt lgkmcnt(2)
	v_mul_f32_e32 v42, v174, v86
	v_fma_f32 v85, v44, v71, -v42
	v_mul_f32_e32 v42, v174, v87
	v_fma_f32 v86, v45, v70, -v42
	s_waitcnt lgkmcnt(1)
	v_mul_f32_e32 v42, v174, v88
	v_fma_f32 v87, v46, v69, -v42
	v_mul_f32_e32 v42, v174, v89
	v_fma_f32 v88, v47, v68, -v42
	s_waitcnt lgkmcnt(0)
	v_mul_f32_e32 v42, v174, v90
	v_fma_f32 v89, v48, v67, -v42
	ds_read2st64_b32 v[42:43], v74 offset0:32 offset1:33
	v_mul_f32_e32 v44, v174, v91
	v_fma_f32 v90, v49, v66, -v44
	ds_read2st64_b32 v[44:45], v74 offset0:34 offset1:35
	ds_read2st64_b32 v[46:47], v74 offset0:36 offset1:37
	ds_read2st64_b32 v[48:49], v74 offset0:38 offset1:39
	v_lshlrev_b32_e32 v98, 1, v176
	s_waitcnt lgkmcnt(3)
	v_mul_f32_e32 v42, v174, v42
	v_fma_f32 v42, v18, v82, -v42
	v_mul_f32_e32 v18, v174, v43
	v_fma_f32 v43, v19, v80, -v18
	s_waitcnt lgkmcnt(2)
	v_mul_f32_e32 v18, v174, v44
	v_fma_f32 v44, v20, v79, -v18
	v_mul_f32_e32 v18, v174, v45
	v_fma_f32 v45, v21, v78, -v18
	s_waitcnt lgkmcnt(1)
	v_mul_f32_e32 v18, v174, v46
	v_fma_f32 v46, v22, v77, -v18
	v_mul_f32_e32 v18, v174, v47
	v_fma_f32 v47, v23, v81, -v18
	s_waitcnt lgkmcnt(0)
	v_mul_f32_e32 v18, v174, v48
	v_fma_f32 v48, v24, v76, -v18
	ds_read2st64_b32 v[18:19], v74 offset0:40 offset1:41
	v_mul_f32_e32 v20, v174, v49
	v_fma_f32 v49, v25, v75, -v20
	ds_read2st64_b32 v[20:21], v74 offset0:42 offset1:43
	ds_read2st64_b32 v[22:23], v74 offset0:44 offset1:45
	ds_read2st64_b32 v[24:25], v74 offset0:46 offset1:47
	s_waitcnt lgkmcnt(3)
	v_mul_f32_e32 v18, v174, v18
	v_fma_f32 v26, v26, v73, -v18
	v_mul_f32_e32 v18, v174, v19
	v_fma_f32 v27, v27, v72, -v18
	s_waitcnt lgkmcnt(2)
	v_mul_f32_e32 v18, v174, v20
	v_fma_f32 v28, v28, v71, -v18
	v_mul_f32_e32 v18, v174, v21
	v_fma_f32 v29, v29, v70, -v18
	s_waitcnt lgkmcnt(1)
	v_mul_f32_e32 v18, v174, v22
	v_fma_f32 v30, v30, v69, -v18
	v_mul_f32_e32 v18, v174, v23
	v_fma_f32 v31, v31, v68, -v18
	s_waitcnt lgkmcnt(0)
	v_mul_f32_e32 v18, v174, v24
	v_fma_f32 v32, v32, v67, -v18
	ds_read2st64_b32 v[18:19], v74 offset0:48 offset1:49
	v_mul_f32_e32 v20, v174, v25
	v_fma_f32 v33, v33, v66, -v20
	ds_read2st64_b32 v[20:21], v74 offset0:50 offset1:51
	ds_read2st64_b32 v[22:23], v74 offset0:52 offset1:53
	ds_read2st64_b32 v[24:25], v74 offset0:54 offset1:55
	s_waitcnt lgkmcnt(3)
	v_mul_f32_e32 v18, v174, v18
	v_fma_f32 v18, v2, v82, -v18
	v_mul_f32_e32 v2, v174, v19
	v_fma_f32 v19, v3, v80, -v2
	s_waitcnt lgkmcnt(2)
	v_mul_f32_e32 v2, v174, v20
	v_fma_f32 v20, v4, v79, -v2
	v_mul_f32_e32 v2, v174, v21
	v_fma_f32 v21, v5, v78, -v2
	s_waitcnt lgkmcnt(1)
	v_mul_f32_e32 v2, v174, v22
	v_fma_f32 v22, v6, v77, -v2
	v_mul_f32_e32 v2, v174, v23
	v_fma_f32 v23, v7, v81, -v2
	s_waitcnt lgkmcnt(0)
; __device__ __forceinline__ void store16_wt(void* p, u32x4 v) { asm volatile("global_store_dwordx4 %0, %1, off sc1\n\ts_nop 1" :: "v"(p), "v"(v) : "memory"); }
; #define LAS __attribute__((address_space(3)))
; __device__ __forceinline__ int crow(int r, int hi) { return (r & 3) + 8 * (r >> 2) + 4 * hi; }
; __device__ __forceinline__ unsigned cvtpk_s(float lo, float hi) { return pg8::cvt_pk_bf16(lo, hi); }
; __device__ __forceinline__ void attn_unit(int b, int h, int qb, const bf16* Q, const bf16* K, const bf16* V, bf16* MIX, LAS unsigned char* lds, const LAS float* BLh, float lam, LAS float* als, gu32* rdy4) {
;     ...
;             for (int r = 0; r < 16; ++r) o[d][r] = o[d][r] * rl[r] - lam * stg[(d * 16 + r) * 64 + lane];
;         asm volatile("s_waitcnt lgkmcnt(0)" ::: "memory");
; #pragma unroll
;         for (int d = 0; d < 4; ++d)
; #pragma unroll
;             for (int r = 0; r < 16; ++r) stg[crow(r, hi) * 132 + d * 32 + r32] = o[d][r];
;         asm volatile("s_waitcnt lgkmcnt(0)" ::: "memory");
;         bf16* Mw = MIX + (rowbase + q0 + qw * 32) * 1024 + h * 128;
; #pragma unroll
;         for (int ps = 0; ps < 8; ++ps) { const int row = ps * 4 + (lane >> 4), seg = lane & 15;
;             const f32x4 a = *(const LAS f32x4*)(stg + row * 132 + 8 * seg), c = *(const LAS f32x4*)(stg + row * 132 + 8 * seg + 4);
;             float ss = (a[0] * a[0] + a[1] * a[1]) + (a[2] * a[2] + a[3] * a[3]) + (c[0] * c[0] + c[1] * c[1]) + (c[2] * c[2] + c[3] * c[3]);
;             ss += __shfl_xor(ss, 1); ss += __shfl_xor(ss, 2); ss += __shfl_xor(ss, 4); ss += __shfl_xor(ss, 8);
;             const float rstd = rsqrtf(ss * (1.0f / 128.0f) + EPSF);
;             pg8::store16_wt(Mw + (long)row * 1024 + 8 * seg, (v4u){cvtpk_s(a[0] * rstd, a[1] * rstd), cvtpk_s(a[2] * rstd, a[3] * rstd), cvtpk_s(c[0] * rstd, c[1] * rstd), cvtpk_s(c[2] * rstd, c[3] * rstd)}); }
	v_mul_f32_e32 v2, v174, v24
	v_fma_f32 v24, v8, v76, -v2
	v_mul_f32_e32 v4, v174, v25
	ds_read2st64_b32 v[2:3], v74 offset0:56 offset1:57
	v_fma_f32 v25, v9, v75, -v4
	ds_read2st64_b32 v[4:5], v74 offset0:58 offset1:59
	ds_read2st64_b32 v[6:7], v74 offset0:60 offset1:61
	ds_read2st64_b32 v[8:9], v74 offset0:62 offset1:63
	s_waitcnt lgkmcnt(0)
	s_waitcnt lgkmcnt(3)
	v_mul_f32_e32 v2, v174, v2
	v_fma_f32 v2, v10, v73, -v2
	v_mul_f32_e32 v3, v174, v3
	s_waitcnt lgkmcnt(2)
	v_mul_f32_e32 v4, v174, v4
	v_mul_f32_e32 v5, v174, v5
	s_waitcnt lgkmcnt(1)
	v_mul_f32_e32 v6, v174, v6
	v_mul_f32_e32 v7, v174, v7
	s_waitcnt lgkmcnt(0)
	v_mul_f32_e32 v9, v174, v9
	v_add3_u32 v10, s18, v172, v205
	v_fma_f32 v3, v11, v72, -v3
	v_fma_f32 v4, v12, v71, -v4
	v_fma_f32 v5, v13, v70, -v5
	v_fma_f32 v6, v14, v69, -v6
	v_fma_f32 v7, v15, v68, -v7
	v_mul_f32_e32 v8, v174, v8
	v_fma_f32 v9, v17, v66, -v9
	v_add_u32_e32 v11, 0x400, v10
	v_add_u32_e32 v12, 0x1000, v10
	v_add_u32_e32 v13, 0x1400, v10
	v_add_u32_e32 v14, 0x2000, v10
	v_add_u32_e32 v15, 0x2400, v10
	v_add_u32_e32 v17, 0x3200, v10
	v_fma_f32 v8, v16, v67, -v8
	ds_write2_b32 v10, v50, v34 offset1:32
	ds_write2_b32 v10, v51, v35 offset0:132 offset1:164
	ds_write2_b32 v11, v52, v36 offset0:8 offset1:40
	ds_write2_b32 v11, v53, v37 offset0:140 offset1:172
	ds_write2_b32 v12, v54, v38 offset0:32 offset1:64
	ds_write2_b32 v12, v55, v39 offset0:164 offset1:196
	ds_write2_b32 v13, v56, v40 offset0:40 offset1:72
	ds_write2_b32 v13, v57, v41 offset0:172 offset1:204
	ds_write2_b32 v14, v58, v83 offset0:64 offset1:96
	ds_write2_b32 v14, v59, v84 offset0:196 offset1:228
	ds_write2_b32 v15, v60, v85 offset0:72 offset1:104
	ds_write2_b32 v15, v61, v86 offset0:204 offset1:236
	v_add_u32_e32 v16, 0x3000, v10
	ds_write2_b32 v17, v63, v88 offset0:100 offset1:132
	v_add_u32_e32 v17, 0x3400, v10
	v_add_u32_e32 v34, 0x3600, v10
	ds_write2_b32 v16, v62, v87 offset0:96 offset1:128
	ds_write2_b32 v17, v64, v89 offset0:104 offset1:136
	ds_write2_b32 v34, v65, v90 offset0:108 offset1:140
	ds_write2_b32 v10, v42, v18 offset0:64 offset1:96
	ds_write2_b32 v10, v43, v19 offset0:196 offset1:228
	ds_write2_b32 v11, v44, v20 offset0:72 offset1:104
	ds_write2_b32 v11, v45, v21 offset0:204 offset1:236
	ds_write2_b32 v12, v46, v22 offset0:96 offset1:128
	v_add_u32_e32 v11, 0x1200, v10
	ds_write2_b32 v11, v47, v23 offset0:100 offset1:132
	ds_write2_b32 v13, v48, v24 offset0:104 offset1:136
	v_add_u32_e32 v11, 0x1600, v10
	ds_write2_b32 v11, v49, v25 offset0:108 offset1:140
	ds_write2_b32 v14, v26, v2 offset0:128 offset1:160
	ds_write2_b32 v15, v27, v3 offset0:4 offset1:36
	ds_write2_b32 v15, v28, v4 offset0:136 offset1:168
	v_add_u32_e32 v2, 0x2800, v10
	ds_write2_b32 v2, v29, v5 offset0:12 offset1:44
	ds_write2_b32 v16, v30, v6 offset0:160 offset1:192
	ds_write2_b32 v17, v31, v7 offset0:36 offset1:68
	ds_write2_b32 v17, v32, v8 offset0:168 offset1:200
	v_add_u32_e32 v2, 0x3800, v10
	ds_write2_b32 v2, v33, v9 offset0:44 offset1:76
	v_lshlrev_b32_e32 v2, 2, v176
	s_waitcnt lgkmcnt(0)
	v_add3_u32 v22, s18, v2, v207
	ds_read_b128 v[6:9], v22
	ds_read_b128 v[10:13], v22 offset:16
	v_and_b32_e32 v4, 64, v1
	v_xor_b32_e32 v3, 1, v1
	v_add_u32_e32 v5, 64, v4
	v_cmp_lt_i32_e32 vcc, v3, v5
	s_waitcnt lgkmcnt(1)
	v_pk_mul_f32 v[14:15], v[6:7], v[6:7]
	s_add_u32 s18, s30, s19
	v_cndmask_b32_e32 v2, v1, v3, vcc
	v_lshlrev_b32_e32 v4, 2, v2
	v_pk_mul_f32 v[2:3], v[8:9], v[8:9]
	s_addc_u32 s19, s31, 0
	v_pk_mov_b32 v[16:17], v[14:15], v[2:3] op_sel:[1,0]
	v_mov_b32_e32 v15, v3
	v_pk_add_f32 v[2:3], v[16:17], v[14:15]
	s_waitcnt lgkmcnt(0)
	v_pk_mul_f32 v[14:15], v[12:13], v[12:13]
	v_pk_mul_f32 v[16:17], v[10:11], v[10:11]
	v_mov_b32_e32 v18, v14
	v_mov_b32_e32 v19, v16
	v_mov_b32_e32 v16, v15
	v_pk_add_f32 v[14:15], v[18:19], v[16:17]
	v_add_f32_e32 v2, v2, v3
	v_add_f32_e32 v2, v2, v15
	v_add_f32_e32 v2, v14, v2
	s_nop 1
	v_mov_b32_dpp v3, v2 quad_perm:[1,0,3,2] row_mask:0xf bank_mask:0xf
	v_xor_b32_e32 v14, 2, v1
	v_cmp_lt_i32_e32 vcc, v14, v5
	s_lshl_b32 s20, s20, 1
	s_add_u32 s18, s18, s20
	v_cndmask_b32_e32 v14, v1, v14, vcc
	v_lshlrev_b32_e32 v23, 2, v14
	s_waitcnt lgkmcnt(0)
	v_add_f32_e32 v2, v2, v3
	s_nop 1
	v_mov_b32_dpp v3, v2 quad_perm:[2,3,0,1] row_mask:0xf bank_mask:0xf
	v_xor_b32_e32 v14, 4, v1
	v_cmp_lt_i32_e32 vcc, v14, v5
	s_addc_u32 s19, s19, 0
	s_waitcnt lgkmcnt(0)
	v_add_f32_e32 v2, v2, v3
	v_cndmask_b32_e32 v14, v1, v14, vcc
	v_lshlrev_b32_e32 v24, 2, v14
	v_mov_b32_dpp v3, v2 row_shr:4 row_mask:0xf bank_mask:0xa
	v_mov_b32_dpp v3, v2 row_shl:4 row_mask:0xf bank_mask:0x5
	v_xor_b32_e32 v14, 8, v1
	v_cmp_lt_i32_e32 vcc, v14, v5
	s_waitcnt lgkmcnt(0)
	v_add_f32_e32 v2, v2, v3
	v_cndmask_b32_e32 v5, v1, v14, vcc
	v_lshlrev_b32_e32 v5, 2, v5
	v_mov_b32_dpp v3, v2 row_ror:8 row_mask:0xf bank_mask:0xf
	s_waitcnt lgkmcnt(0)
	v_add_f32_e32 v2, v2, v3
	v_fmamk_f32 v2, v2, 0x3c000000, v242
	v_mul_f32_e32 v3, 0x4b800000, v2
	v_cmp_gt_f32_e32 vcc, s84, v2
	s_nop 1
	v_cndmask_b32_e32 v2, v2, v3, vcc
	v_rsq_f32_e32 v14, v2
	v_lshl_add_u64 v[2:3], s[18:19], 0, v[98:99]
	v_lshl_add_u64 v[16:17], v[178:179], 1, v[2:3]
	v_mul_f32_e32 v15, 0x45800000, v14
	v_cndmask_b32_e32 v14, v14, v15, vcc
	v_pk_mul_f32 v[6:7], v[6:7], v[14:15] op_sel_hi:[1,0]
	v_pk_mul_f32 v[8:9], v[8:9], v[14:15] op_sel_hi:[1,0]
	v_cvt_pk_bf16_f32 v6, v6, v7
	v_cvt_pk_bf16_f32 v7, v8, v9
	v_pk_mul_f32 v[8:9], v[10:11], v[14:15] op_sel_hi:[1,0]
	v_pk_mul_f32 v[10:11], v[12:13], v[14:15] op_sel_hi:[1,0]
	v_cvt_pk_bf16_f32 v8, v8, v9
	v_cvt_pk_bf16_f32 v9, v10, v11
	global_store_dwordx4 v[16:17], v[6:9], off sc1
	s_nop 1
	ds_read_b128 v[6:9], v22 offset:2112
	ds_read_b128 v[10:13], v22 offset:2128
	s_waitcnt lgkmcnt(1)
; __device__ __forceinline__ void store16_wt(void* p, u32x4 v) { asm volatile("global_store_dwordx4 %0, %1, off sc1\n\ts_nop 1" :: "v"(p), "v"(v) : "memory"); }
; #define LAS __attribute__((address_space(3)))
; __device__ __forceinline__ unsigned cvtpk_s(float lo, float hi) { return pg8::cvt_pk_bf16(lo, hi); }
; __device__ __forceinline__ void attn_unit(int b, int h, int qb, const bf16* Q, const bf16* K, const bf16* V, bf16* MIX, LAS unsigned char* lds, const LAS float* BLh, float lam, LAS float* als, gu32* rdy4) {
;     ...
;         for (int ps = 0; ps < 8; ++ps) { const int row = ps * 4 + (lane >> 4), seg = lane & 15;
;             const f32x4 a = *(const LAS f32x4*)(stg + row * 132 + 8 * seg), c = *(const LAS f32x4*)(stg + row * 132 + 8 * seg + 4);
;             float ss = (a[0] * a[0] + a[1] * a[1]) + (a[2] * a[2] + a[3] * a[3]) + (c[0] * c[0] + c[1] * c[1]) + (c[2] * c[2] + c[3] * c[3]);
;             ss += __shfl_xor(ss, 1); ss += __shfl_xor(ss, 2); ss += __shfl_xor(ss, 4); ss += __shfl_xor(ss, 8);
;             const float rstd = rsqrtf(ss * (1.0f / 128.0f) + EPSF);
;             pg8::store16_wt(Mw + (long)row * 1024 + 8 * seg, (v4u){cvtpk_s(a[0] * rstd, a[1] * rstd), cvtpk_s(a[2] * rstd, a[3] * rstd), cvtpk_s(c[0] * rstd, c[1] * rstd), cvtpk_s(c[2] * rstd, c[3] * rstd)}); }
	v_pk_mul_f32 v[14:15], v[8:9], v[8:9]
	v_pk_mul_f32 v[16:17], v[6:7], v[6:7]
	s_nop 0
	v_pk_mov_b32 v[18:19], v[16:17], v[14:15] op_sel:[1,0]
	v_mov_b32_e32 v17, v15
	v_pk_add_f32 v[14:15], v[18:19], v[16:17]
	s_waitcnt lgkmcnt(0)
	v_pk_mul_f32 v[16:17], v[12:13], v[12:13]
	v_pk_mul_f32 v[18:19], v[10:11], v[10:11]
	v_mov_b32_e32 v20, v16
	v_mov_b32_e32 v21, v18
	v_mov_b32_e32 v18, v17
	v_pk_add_f32 v[16:17], v[20:21], v[18:19]
	v_add_f32_e32 v14, v14, v15
	v_add_f32_e32 v14, v14, v17
	v_add_f32_e32 v14, v16, v14
	s_nop 1
	v_mov_b32_dpp v15, v14 quad_perm:[1,0,3,2] row_mask:0xf bank_mask:0xf
	v_lshl_add_u64 v[16:17], v[180:181], 1, v[2:3]
	s_waitcnt lgkmcnt(0)
	v_add_f32_e32 v14, v14, v15
	s_nop 1
	v_mov_b32_dpp v15, v14 quad_perm:[2,3,0,1] row_mask:0xf bank_mask:0xf
	s_waitcnt lgkmcnt(0)
	v_add_f32_e32 v14, v14, v15
	s_nop 1
	v_mov_b32_dpp v15, v14 row_shr:4 row_mask:0xf bank_mask:0xa
	v_mov_b32_dpp v15, v14 row_shl:4 row_mask:0xf bank_mask:0x5
	s_waitcnt lgkmcnt(0)
	v_add_f32_e32 v14, v14, v15
	s_nop 1
	v_mov_b32_dpp v15, v14 row_ror:8 row_mask:0xf bank_mask:0xf
	s_waitcnt lgkmcnt(0)
	v_add_f32_e32 v14, v14, v15
	v_fmamk_f32 v14, v14, 0x3c000000, v242
	v_mul_f32_e32 v15, 0x4b800000, v14
	v_cmp_gt_f32_e32 vcc, s84, v14
	s_nop 1
	v_cndmask_b32_e32 v14, v14, v15, vcc
	v_rsq_f32_e32 v14, v14
	s_nop 0
	v_mul_f32_e32 v15, 0x45800000, v14
	v_cndmask_b32_e32 v14, v14, v15, vcc
	v_pk_mul_f32 v[6:7], v[6:7], v[14:15] op_sel_hi:[1,0]
	v_pk_mul_f32 v[8:9], v[8:9], v[14:15] op_sel_hi:[1,0]
	v_cvt_pk_bf16_f32 v6, v6, v7
	v_cvt_pk_bf16_f32 v7, v8, v9
	v_pk_mul_f32 v[8:9], v[10:11], v[14:15] op_sel_hi:[1,0]
	v_pk_mul_f32 v[10:11], v[12:13], v[14:15] op_sel_hi:[1,0]
	v_cvt_pk_bf16_f32 v8, v8, v9
	v_cvt_pk_bf16_f32 v9, v10, v11
	global_store_dwordx4 v[16:17], v[6:9], off sc1
	s_nop 1
	ds_read_b128 v[6:9], v22 offset:4224
	ds_read_b128 v[10:13], v22 offset:4240
	s_waitcnt lgkmcnt(1)
	v_pk_mul_f32 v[14:15], v[8:9], v[8:9]
	v_pk_mul_f32 v[16:17], v[6:7], v[6:7]
	s_nop 0
	v_pk_mov_b32 v[18:19], v[16:17], v[14:15] op_sel:[1,0]
	v_mov_b32_e32 v17, v15
	v_pk_add_f32 v[14:15], v[18:19], v[16:17]
	s_waitcnt lgkmcnt(0)
	v_pk_mul_f32 v[16:17], v[12:13], v[12:13]
	v_pk_mul_f32 v[18:19], v[10:11], v[10:11]
	v_mov_b32_e32 v20, v16
	v_mov_b32_e32 v21, v18
	v_mov_b32_e32 v18, v17
	v_pk_add_f32 v[16:17], v[20:21], v[18:19]
	v_add_f32_e32 v14, v14, v15
	v_add_f32_e32 v14, v14, v17
	v_add_f32_e32 v14, v16, v14
	s_nop 1
	v_mov_b32_dpp v15, v14 quad_perm:[1,0,3,2] row_mask:0xf bank_mask:0xf
	v_lshl_add_u64 v[16:17], v[182:183], 1, v[2:3]
	s_waitcnt lgkmcnt(0)
	v_add_f32_e32 v14, v14, v15
	s_nop 1
	v_mov_b32_dpp v15, v14 quad_perm:[2,3,0,1] row_mask:0xf bank_mask:0xf
	s_waitcnt lgkmcnt(0)
	v_add_f32_e32 v14, v14, v15
	s_nop 1
	v_mov_b32_dpp v15, v14 row_shr:4 row_mask:0xf bank_mask:0xa
	v_mov_b32_dpp v15, v14 row_shl:4 row_mask:0xf bank_mask:0x5
	s_waitcnt lgkmcnt(0)
	v_add_f32_e32 v14, v14, v15
	s_nop 1
	v_mov_b32_dpp v15, v14 row_ror:8 row_mask:0xf bank_mask:0xf
	s_waitcnt lgkmcnt(0)
	v_add_f32_e32 v14, v14, v15
	v_fmamk_f32 v14, v14, 0x3c000000, v242
	v_mul_f32_e32 v15, 0x4b800000, v14
	v_cmp_gt_f32_e32 vcc, s84, v14
	s_nop 1
	v_cndmask_b32_e32 v14, v14, v15, vcc
	v_rsq_f32_e32 v14, v14
	s_nop 0
	v_mul_f32_e32 v15, 0x45800000, v14
	v_cndmask_b32_e32 v14, v14, v15, vcc
	v_pk_mul_f32 v[6:7], v[6:7], v[14:15] op_sel_hi:[1,0]
	v_pk_mul_f32 v[8:9], v[8:9], v[14:15] op_sel_hi:[1,0]
	v_cvt_pk_bf16_f32 v6, v6, v7
	v_cvt_pk_bf16_f32 v7, v8, v9
	v_pk_mul_f32 v[8:9], v[10:11], v[14:15] op_sel_hi:[1,0]
	v_pk_mul_f32 v[10:11], v[12:13], v[14:15] op_sel_hi:[1,0]
	v_cvt_pk_bf16_f32 v8, v8, v9
	v_cvt_pk_bf16_f32 v9, v10, v11
	global_store_dwordx4 v[16:17], v[6:9], off sc1
	s_nop 1
	ds_read_b128 v[6:9], v22 offset:6336
	ds_read_b128 v[10:13], v22 offset:6352
	s_waitcnt lgkmcnt(1)
	v_pk_mul_f32 v[14:15], v[8:9], v[8:9]
	v_pk_mul_f32 v[16:17], v[6:7], v[6:7]
	s_nop 0
	v_pk_mov_b32 v[18:19], v[16:17], v[14:15] op_sel:[1,0]
	v_mov_b32_e32 v17, v15
	v_pk_add_f32 v[14:15], v[18:19], v[16:17]
	s_waitcnt lgkmcnt(0)
	v_pk_mul_f32 v[16:17], v[12:13], v[12:13]
	v_pk_mul_f32 v[18:19], v[10:11], v[10:11]
	v_mov_b32_e32 v20, v16
	v_mov_b32_e32 v21, v18
	v_mov_b32_e32 v18, v17
	v_pk_add_f32 v[16:17], v[20:21], v[18:19]
	v_add_f32_e32 v14, v14, v15
	v_add_f32_e32 v14, v14, v17
	v_add_f32_e32 v14, v16, v14
	s_nop 1
	v_mov_b32_dpp v15, v14 quad_perm:[1,0,3,2] row_mask:0xf bank_mask:0xf
	v_lshl_add_u64 v[16:17], v[184:185], 1, v[2:3]
	s_waitcnt lgkmcnt(0)
	v_add_f32_e32 v14, v14, v15
	s_nop 1
	v_mov_b32_dpp v15, v14 quad_perm:[2,3,0,1] row_mask:0xf bank_mask:0xf
	s_waitcnt lgkmcnt(0)
	v_add_f32_e32 v14, v14, v15
	s_nop 1
	v_mov_b32_dpp v15, v14 row_shr:4 row_mask:0xf bank_mask:0xa
	v_mov_b32_dpp v15, v14 row_shl:4 row_mask:0xf bank_mask:0x5
	s_waitcnt lgkmcnt(0)
	v_add_f32_e32 v14, v14, v15
	s_nop 1
	v_mov_b32_dpp v15, v14 row_ror:8 row_mask:0xf bank_mask:0xf
	s_waitcnt lgkmcnt(0)
	v_add_f32_e32 v14, v14, v15
	v_fmamk_f32 v14, v14, 0x3c000000, v242
	v_mul_f32_e32 v15, 0x4b800000, v14
	v_cmp_gt_f32_e32 vcc, s84, v14
	s_nop 1
	v_cndmask_b32_e32 v14, v14, v15, vcc
	v_rsq_f32_e32 v14, v14
	s_nop 0
	v_mul_f32_e32 v15, 0x45800000, v14
	v_cndmask_b32_e32 v14, v14, v15, vcc
	v_pk_mul_f32 v[6:7], v[6:7], v[14:15] op_sel_hi:[1,0]
	v_pk_mul_f32 v[8:9], v[8:9], v[14:15] op_sel_hi:[1,0]
	v_cvt_pk_bf16_f32 v6, v6, v7
	v_cvt_pk_bf16_f32 v7, v8, v9
	v_pk_mul_f32 v[8:9], v[10:11], v[14:15] op_sel_hi:[1,0]
	v_pk_mul_f32 v[10:11], v[12:13], v[14:15] op_sel_hi:[1,0]
	v_cvt_pk_bf16_f32 v8, v8, v9
	v_cvt_pk_bf16_f32 v9, v10, v11
	global_store_dwordx4 v[16:17], v[6:9], off sc1
	s_nop 1
	ds_read_b128 v[6:9], v22 offset:8448
	ds_read_b128 v[10:13], v22 offset:8464
	s_waitcnt lgkmcnt(1)
; __device__ __forceinline__ void store16_wt(void* p, u32x4 v) { asm volatile("global_store_dwordx4 %0, %1, off sc1\n\ts_nop 1" :: "v"(p), "v"(v) : "memory"); }
; #define LAS __attribute__((address_space(3)))
; __device__ __forceinline__ unsigned cvtpk_s(float lo, float hi) { return pg8::cvt_pk_bf16(lo, hi); }
; __device__ __forceinline__ void attn_unit(int b, int h, int qb, const bf16* Q, const bf16* K, const bf16* V, bf16* MIX, LAS unsigned char* lds, const LAS float* BLh, float lam, LAS float* als, gu32* rdy4) {
;     ...
;         for (int ps = 0; ps < 8; ++ps) { const int row = ps * 4 + (lane >> 4), seg = lane & 15;
;             const f32x4 a = *(const LAS f32x4*)(stg + row * 132 + 8 * seg), c = *(const LAS f32x4*)(stg + row * 132 + 8 * seg + 4);
;             float ss = (a[0] * a[0] + a[1] * a[1]) + (a[2] * a[2] + a[3] * a[3]) + (c[0] * c[0] + c[1] * c[1]) + (c[2] * c[2] + c[3] * c[3]);
;             ss += __shfl_xor(ss, 1); ss += __shfl_xor(ss, 2); ss += __shfl_xor(ss, 4); ss += __shfl_xor(ss, 8);
;             const float rstd = rsqrtf(ss * (1.0f / 128.0f) + EPSF);
;             pg8::store16_wt(Mw + (long)row * 1024 + 8 * seg, (v4u){cvtpk_s(a[0] * rstd, a[1] * rstd), cvtpk_s(a[2] * rstd, a[3] * rstd), cvtpk_s(c[0] * rstd, c[1] * rstd), cvtpk_s(c[2] * rstd, c[3] * rstd)}); }
	v_pk_mul_f32 v[14:15], v[8:9], v[8:9]
	v_pk_mul_f32 v[16:17], v[6:7], v[6:7]
	s_nop 0
	v_pk_mov_b32 v[18:19], v[16:17], v[14:15] op_sel:[1,0]
	v_mov_b32_e32 v17, v15
	v_pk_add_f32 v[14:15], v[18:19], v[16:17]
	s_waitcnt lgkmcnt(0)
	v_pk_mul_f32 v[16:17], v[12:13], v[12:13]
	v_pk_mul_f32 v[18:19], v[10:11], v[10:11]
	v_mov_b32_e32 v20, v16
	v_mov_b32_e32 v21, v18
	v_mov_b32_e32 v18, v17
	v_pk_add_f32 v[16:17], v[20:21], v[18:19]
	v_add_f32_e32 v14, v14, v15
	v_add_f32_e32 v14, v14, v17
	v_add_f32_e32 v14, v16, v14
	s_nop 1
	v_mov_b32_dpp v15, v14 quad_perm:[1,0,3,2] row_mask:0xf bank_mask:0xf
	v_lshl_add_u64 v[16:17], v[186:187], 1, v[2:3]
	s_waitcnt lgkmcnt(0)
	v_add_f32_e32 v14, v14, v15
	s_nop 1
	v_mov_b32_dpp v15, v14 quad_perm:[2,3,0,1] row_mask:0xf bank_mask:0xf
	s_waitcnt lgkmcnt(0)
	v_add_f32_e32 v14, v14, v15
	s_nop 1
	v_mov_b32_dpp v15, v14 row_shr:4 row_mask:0xf bank_mask:0xa
	v_mov_b32_dpp v15, v14 row_shl:4 row_mask:0xf bank_mask:0x5
	s_waitcnt lgkmcnt(0)
	v_add_f32_e32 v14, v14, v15
	s_nop 1
	v_mov_b32_dpp v15, v14 row_ror:8 row_mask:0xf bank_mask:0xf
	s_waitcnt lgkmcnt(0)
	v_add_f32_e32 v14, v14, v15
	v_fmamk_f32 v14, v14, 0x3c000000, v242
	v_mul_f32_e32 v15, 0x4b800000, v14
	v_cmp_gt_f32_e32 vcc, s84, v14
	s_nop 1
	v_cndmask_b32_e32 v14, v14, v15, vcc
	v_rsq_f32_e32 v14, v14
	s_nop 0
	v_mul_f32_e32 v15, 0x45800000, v14
	v_cndmask_b32_e32 v14, v14, v15, vcc
	v_pk_mul_f32 v[6:7], v[6:7], v[14:15] op_sel_hi:[1,0]
	v_pk_mul_f32 v[8:9], v[8:9], v[14:15] op_sel_hi:[1,0]
	v_cvt_pk_bf16_f32 v6, v6, v7
	v_cvt_pk_bf16_f32 v7, v8, v9
	v_pk_mul_f32 v[8:9], v[10:11], v[14:15] op_sel_hi:[1,0]
	v_pk_mul_f32 v[10:11], v[12:13], v[14:15] op_sel_hi:[1,0]
	v_cvt_pk_bf16_f32 v8, v8, v9
	v_cvt_pk_bf16_f32 v9, v10, v11
	global_store_dwordx4 v[16:17], v[6:9], off sc1
	s_nop 1
	ds_read_b128 v[6:9], v22 offset:10560
	ds_read_b128 v[10:13], v22 offset:10576
	s_waitcnt lgkmcnt(1)
	v_pk_mul_f32 v[14:15], v[8:9], v[8:9]
	v_pk_mul_f32 v[16:17], v[6:7], v[6:7]
	s_nop 0
	v_pk_mov_b32 v[18:19], v[16:17], v[14:15] op_sel:[1,0]
	v_mov_b32_e32 v17, v15
	v_pk_add_f32 v[14:15], v[18:19], v[16:17]
	s_waitcnt lgkmcnt(0)
	v_pk_mul_f32 v[16:17], v[12:13], v[12:13]
	v_pk_mul_f32 v[18:19], v[10:11], v[10:11]
	v_mov_b32_e32 v20, v16
	v_mov_b32_e32 v21, v18
	v_mov_b32_e32 v18, v17
	v_pk_add_f32 v[16:17], v[20:21], v[18:19]
	v_add_f32_e32 v14, v14, v15
	v_add_f32_e32 v14, v14, v17
	v_add_f32_e32 v14, v16, v14
	s_nop 1
	v_mov_b32_dpp v15, v14 quad_perm:[1,0,3,2] row_mask:0xf bank_mask:0xf
	v_lshl_add_u64 v[16:17], v[188:189], 1, v[2:3]
	s_waitcnt lgkmcnt(0)
	v_add_f32_e32 v14, v14, v15
	s_nop 1
	v_mov_b32_dpp v15, v14 quad_perm:[2,3,0,1] row_mask:0xf bank_mask:0xf
	s_waitcnt lgkmcnt(0)
	v_add_f32_e32 v14, v14, v15
	s_nop 1
	v_mov_b32_dpp v15, v14 row_shr:4 row_mask:0xf bank_mask:0xa
	v_mov_b32_dpp v15, v14 row_shl:4 row_mask:0xf bank_mask:0x5
	s_waitcnt lgkmcnt(0)
	v_add_f32_e32 v14, v14, v15
	s_nop 1
	v_mov_b32_dpp v15, v14 row_ror:8 row_mask:0xf bank_mask:0xf
	s_waitcnt lgkmcnt(0)
	v_add_f32_e32 v14, v14, v15
	v_fmamk_f32 v14, v14, 0x3c000000, v242
	v_mul_f32_e32 v15, 0x4b800000, v14
	v_cmp_gt_f32_e32 vcc, s84, v14
	s_nop 1
	v_cndmask_b32_e32 v14, v14, v15, vcc
	v_rsq_f32_e32 v14, v14
	s_nop 0
	v_mul_f32_e32 v15, 0x45800000, v14
	v_cndmask_b32_e32 v14, v14, v15, vcc
	v_pk_mul_f32 v[6:7], v[6:7], v[14:15] op_sel_hi:[1,0]
	v_pk_mul_f32 v[8:9], v[8:9], v[14:15] op_sel_hi:[1,0]
	v_cvt_pk_bf16_f32 v6, v6, v7
	v_cvt_pk_bf16_f32 v7, v8, v9
	v_pk_mul_f32 v[8:9], v[10:11], v[14:15] op_sel_hi:[1,0]
	v_pk_mul_f32 v[10:11], v[12:13], v[14:15] op_sel_hi:[1,0]
	v_cvt_pk_bf16_f32 v8, v8, v9
	v_cvt_pk_bf16_f32 v9, v10, v11
	global_store_dwordx4 v[16:17], v[6:9], off sc1
	s_nop 1
	ds_read_b128 v[6:9], v22 offset:12672
	ds_read_b128 v[10:13], v22 offset:12688
	s_waitcnt lgkmcnt(1)
	v_pk_mul_f32 v[14:15], v[8:9], v[8:9]
	v_pk_mul_f32 v[16:17], v[6:7], v[6:7]
	s_nop 0
	v_pk_mov_b32 v[18:19], v[16:17], v[14:15] op_sel:[1,0]
	v_mov_b32_e32 v17, v15
	v_pk_add_f32 v[14:15], v[18:19], v[16:17]
	s_waitcnt lgkmcnt(0)
; __device__ __forceinline__ void store16_wt(void* p, u32x4 v) { asm volatile("global_store_dwordx4 %0, %1, off sc1\n\ts_nop 1" :: "v"(p), "v"(v) : "memory"); }
; #define LAS __attribute__((address_space(3)))
; __device__ __forceinline__ unsigned cvtpk_s(float lo, float hi) { return pg8::cvt_pk_bf16(lo, hi); }
; __device__ __forceinline__ void attn_unit(int b, int h, int qb, const bf16* Q, const bf16* K, const bf16* V, bf16* MIX, LAS unsigned char* lds, const LAS float* BLh, float lam, LAS float* als, gu32* rdy4) {
;     ...
;         for (int ps = 0; ps < 8; ++ps) { const int row = ps * 4 + (lane >> 4), seg = lane & 15;
;             const f32x4 a = *(const LAS f32x4*)(stg + row * 132 + 8 * seg), c = *(const LAS f32x4*)(stg + row * 132 + 8 * seg + 4);
;             float ss = (a[0] * a[0] + a[1] * a[1]) + (a[2] * a[2] + a[3] * a[3]) + (c[0] * c[0] + c[1] * c[1]) + (c[2] * c[2] + c[3] * c[3]);
;             ss += __shfl_xor(ss, 1); ss += __shfl_xor(ss, 2); ss += __shfl_xor(ss, 4); ss += __shfl_xor(ss, 8);
;             const float rstd = rsqrtf(ss * (1.0f / 128.0f) + EPSF);
;             pg8::store16_wt(Mw + (long)row * 1024 + 8 * seg, (v4u){cvtpk_s(a[0] * rstd, a[1] * rstd), cvtpk_s(a[2] * rstd, a[3] * rstd), cvtpk_s(c[0] * rstd, c[1] * rstd), cvtpk_s(c[2] * rstd, c[3] * rstd)}); }
;         asm volatile("s_waitcnt vmcnt(0)" ::: "memory");
;         if (lane == 0) __hip_atomic_fetch_add(rdy4 + 64 * (b * 32 + (qb >> 1)), 1u, RLX_AGENT);
	v_pk_mul_f32 v[16:17], v[12:13], v[12:13]
	v_pk_mul_f32 v[18:19], v[10:11], v[10:11]
	v_mov_b32_e32 v20, v16
	v_mov_b32_e32 v21, v18
	v_mov_b32_e32 v18, v17
	v_pk_add_f32 v[16:17], v[20:21], v[18:19]
	v_add_f32_e32 v14, v14, v15
	v_add_f32_e32 v14, v14, v17
	v_add_f32_e32 v14, v16, v14
	s_nop 1
	v_mov_b32_dpp v15, v14 quad_perm:[1,0,3,2] row_mask:0xf bank_mask:0xf
	v_lshl_add_u64 v[16:17], v[190:191], 1, v[2:3]
	s_waitcnt lgkmcnt(0)
	v_add_f32_e32 v14, v14, v15
	s_nop 1
	v_mov_b32_dpp v15, v14 quad_perm:[2,3,0,1] row_mask:0xf bank_mask:0xf
	s_waitcnt lgkmcnt(0)
	v_add_f32_e32 v14, v14, v15
	s_nop 1
	v_mov_b32_dpp v15, v14 row_shr:4 row_mask:0xf bank_mask:0xa
	v_mov_b32_dpp v15, v14 row_shl:4 row_mask:0xf bank_mask:0x5
	s_waitcnt lgkmcnt(0)
	v_add_f32_e32 v14, v14, v15
	s_nop 1
	v_mov_b32_dpp v15, v14 row_ror:8 row_mask:0xf bank_mask:0xf
	s_waitcnt lgkmcnt(0)
	v_add_f32_e32 v14, v14, v15
	v_fmamk_f32 v14, v14, 0x3c000000, v242
	v_mul_f32_e32 v15, 0x4b800000, v14
	v_cmp_gt_f32_e32 vcc, s84, v14
	s_nop 1
	v_cndmask_b32_e32 v14, v14, v15, vcc
	v_rsq_f32_e32 v14, v14
	s_nop 0
	v_mul_f32_e32 v15, 0x45800000, v14
	v_cndmask_b32_e32 v14, v14, v15, vcc
	v_pk_mul_f32 v[6:7], v[6:7], v[14:15] op_sel_hi:[1,0]
	v_pk_mul_f32 v[8:9], v[8:9], v[14:15] op_sel_hi:[1,0]
	v_cvt_pk_bf16_f32 v6, v6, v7
	v_cvt_pk_bf16_f32 v7, v8, v9
	v_pk_mul_f32 v[8:9], v[10:11], v[14:15] op_sel_hi:[1,0]
	v_pk_mul_f32 v[10:11], v[12:13], v[14:15] op_sel_hi:[1,0]
	v_cvt_pk_bf16_f32 v8, v8, v9
	v_cvt_pk_bf16_f32 v9, v10, v11
	global_store_dwordx4 v[16:17], v[6:9], off sc1
	s_nop 1
	ds_read_b128 v[6:9], v22 offset:14784
	ds_read_b128 v[10:13], v22 offset:14800
	s_waitcnt lgkmcnt(1)
	v_pk_mul_f32 v[14:15], v[8:9], v[8:9]
	v_pk_mul_f32 v[16:17], v[6:7], v[6:7]
	s_nop 0
	v_pk_mov_b32 v[18:19], v[16:17], v[14:15] op_sel:[1,0]
	v_mov_b32_e32 v17, v15
	v_pk_add_f32 v[14:15], v[18:19], v[16:17]
	s_waitcnt lgkmcnt(0)
	v_pk_mul_f32 v[16:17], v[12:13], v[12:13]
	v_pk_mul_f32 v[18:19], v[10:11], v[10:11]
	v_mov_b32_e32 v20, v16
	v_mov_b32_e32 v21, v18
	v_mov_b32_e32 v18, v17
	v_pk_add_f32 v[16:17], v[20:21], v[18:19]
	v_add_f32_e32 v14, v14, v15
	v_add_f32_e32 v14, v14, v17
	v_add_f32_e32 v14, v16, v14
	s_nop 1
	v_mov_b32_dpp v4, v14 quad_perm:[1,0,3,2] row_mask:0xf bank_mask:0xf
	v_lshl_add_u64 v[16:17], v[192:193], 1, v[2:3]
	s_waitcnt lgkmcnt(0)
	v_add_f32_e32 v4, v14, v4
	s_nop 1
	v_mov_b32_dpp v14, v4 quad_perm:[2,3,0,1] row_mask:0xf bank_mask:0xf
	s_waitcnt lgkmcnt(0)
	v_add_f32_e32 v4, v4, v14
	s_nop 1
	v_mov_b32_dpp v14, v4 row_shr:4 row_mask:0xf bank_mask:0xa
	v_mov_b32_dpp v14, v4 row_shl:4 row_mask:0xf bank_mask:0x5
	s_waitcnt lgkmcnt(0)
	v_add_f32_e32 v4, v4, v14
	s_nop 1
	v_mov_b32_dpp v5, v4 row_ror:8 row_mask:0xf bank_mask:0xf
	s_waitcnt lgkmcnt(0)
	v_add_f32_e32 v4, v4, v5
	v_fmamk_f32 v4, v4, 0x3c000000, v242
	v_mul_f32_e32 v5, 0x4b800000, v4
	v_cmp_gt_f32_e32 vcc, s84, v4
	s_nop 1
	v_cndmask_b32_e32 v4, v4, v5, vcc
	v_rsq_f32_e32 v4, v4
	s_nop 0
	v_mul_f32_e32 v5, 0x45800000, v4
	v_cndmask_b32_e32 v14, v4, v5, vcc
	v_pk_mul_f32 v[2:3], v[6:7], v[14:15] op_sel_hi:[1,0]
	v_pk_mul_f32 v[4:5], v[8:9], v[14:15] op_sel_hi:[1,0]
	v_cvt_pk_bf16_f32 v2, v2, v3
	v_cvt_pk_bf16_f32 v3, v4, v5
	v_pk_mul_f32 v[4:5], v[10:11], v[14:15] op_sel_hi:[1,0]
	v_pk_mul_f32 v[6:7], v[12:13], v[14:15] op_sel_hi:[1,0]
	v_cvt_pk_bf16_f32 v4, v4, v5
	v_cvt_pk_bf16_f32 v5, v6, v7
	global_store_dwordx4 v[16:17], v[2:5], off sc1
	s_nop 1
	s_waitcnt vmcnt(0)
	s_and_saveexec_b64 s[18:19], s[6:7]
	s_cbranch_execz .LBB0_651
	s_mov_b64 s[20:21], exec
	v_mbcnt_lo_u32_b32 v2, s20, 0
	v_mbcnt_hi_u32_b32 v2, s21, v2
	v_cmp_eq_u32_e32 vcc, 0, v2
	s_and_b64 s[22:23], exec, vcc
	s_mov_b64 exec, s[22:23]
	s_cbranch_execz .LBB0_651
	s_and_b32 s22, s66, 0x1f00
	s_or_b32 s22, s65, s22
	s_bcnt1_i32_b64 s20, s[20:21]
	v_mov_b32_e32 v2, s22
	v_mov_b32_e32 v3, s20
	global_atomic_add v2, v3, s[34:35]
